# nt cache hint on the read-once x loads of the P0 rmsnorm stream (on top of v30)
# speedup vs baseline: 1.1147x; 1.0087x over previous
; __device__ __forceinline__ void p0_prologue(const Args& a, LAS unsigned char* ldsb, int G, int c, const int wid_s) {
;     ...
;   for (int m0 = gw * 4; m0 < MROWS; m0 += NGW * 4) {
;     f32x4 v[4][4]; float ss[4];
; #pragma unroll
;     for (int rr = 0; rr < 4; ++rr) { const f32x4* xr = (const f32x4*)(x + (size_t)(m0 + rr) * DM) + lane;
; #pragma unroll
;       for (int q = 0; q < 4; ++q) v[rr][q] = xr[64 * q]; }
; #pragma unroll
;     for (int rr = 0; rr < 4; ++rr) { float s = 0.f;
; #pragma unroll
;       for (int q = 0; q < 4; ++q) s += (v[rr][q].x * v[rr][q].x + v[rr][q].y * v[rr][q].y) + (v[rr][q].z * v[rr][q].z + v[rr][q].w * v[rr][q].w);
;       ss[rr] = s; }
; #pragma unroll
;     for (int o = 1; o < 64; o <<= 1) {
; #pragma unroll
;       for (int rr = 0; rr < 4; ++rr) ss[rr] += __shfl_xor(ss[rr], o); }
; #pragma unroll
.LBB0_94:
	v_add_co_u32_e32 v38, vcc, 0xffffd000, v36
	global_load_dwordx4 v[28:31], v[36:37], off offset:-3072 nt
	global_load_dwordx4 v[24:27], v[36:37], off offset:-2048 nt
	global_load_dwordx4 v[20:23], v[36:37], off offset:-1024 nt
	global_load_dwordx4 v[16:19], v[36:37], off nt
	v_addc_co_u32_e32 v39, vcc, -1, v37, vcc
	v_add_co_u32_e32 v80, vcc, 0xffffe000, v36
	global_load_dwordx4 v[48:51], v[38:39], off offset:-3072 nt
	global_load_dwordx4 v[52:55], v[38:39], off offset:-2048 nt
	global_load_dwordx4 v[56:59], v[38:39], off offset:-1024 nt
	global_load_dwordx4 v[60:63], v[38:39], off nt
	v_addc_co_u32_e32 v81, vcc, -1, v37, vcc
	v_add_co_u32_e32 v38, vcc, 0xfffff000, v36
	global_load_dwordx4 v[64:67], v[80:81], off offset:-3072 nt
	global_load_dwordx4 v[68:71], v[80:81], off offset:-2048 nt
	global_load_dwordx4 v[72:75], v[80:81], off offset:-1024 nt
	global_load_dwordx4 v[76:79], v[80:81], off nt
	v_addc_co_u32_e32 v39, vcc, -1, v37, vcc
	global_load_dwordx4 v[80:83], v[38:39], off offset:-3072 nt
	global_load_dwordx4 v[84:87], v[38:39], off offset:-2048 nt
	global_load_dwordx4 v[88:91], v[38:39], off offset:-1024 nt
	global_load_dwordx4 v[92:95], v[36:37], off offset:-4096 nt
	v_add_co_u32_e64 v40, s[0:1], s3, v34
	v_add_u32_e32 v32, s6, v32
	s_nop 0
	v_addc_co_u32_e64 v41, s[0:1], -1, v35, s[0:1]
	v_cmp_lt_i32_e64 s[0:1], s7, v32
	s_or_b64 s[22:23], s[0:1], s[22:23]
	v_lshl_add_u64 v[36:37], v[36:37], 0, s[16:17]
	s_waitcnt vmcnt(15)
	v_mul_f32_e32 v38, v29, v29
	v_mul_f32_e32 v39, v31, v31
	s_waitcnt vmcnt(14)
	v_mul_f32_e32 v96, v25, v25
	v_mul_f32_e32 v97, v27, v27
	s_waitcnt vmcnt(13)
	v_mul_f32_e32 v98, v21, v21
	v_mul_f32_e32 v99, v23, v23
	v_fmac_f32_e32 v38, v28, v28
	v_fmac_f32_e32 v39, v30, v30
	v_fmac_f32_e32 v96, v24, v24
	v_fmac_f32_e32 v97, v26, v26
	v_fmac_f32_e32 v98, v20, v20
	v_fmac_f32_e32 v99, v22, v22
	s_waitcnt vmcnt(11)
	v_mul_f32_e32 v102, v49, v49
	v_mul_f32_e32 v103, v51, v51
	s_waitcnt vmcnt(10)
	v_mul_f32_e32 v104, v53, v53
	v_mul_f32_e32 v105, v55, v55
	v_mul_f32_e32 v100, v17, v17
	v_mul_f32_e32 v101, v19, v19
	s_waitcnt vmcnt(9)
	v_mul_f32_e32 v106, v57, v57
	v_add_f32_e32 v38, v38, v39
	v_mul_f32_e32 v39, v59, v59
	v_add_f32_e32 v96, v96, v97
	s_waitcnt vmcnt(8)
	v_mul_f32_e32 v97, v61, v61
	v_add_f32_e32 v98, v98, v99
	v_mul_f32_e32 v99, v63, v63
	v_fmac_f32_e32 v102, v48, v48
	v_fmac_f32_e32 v103, v50, v50
	v_fmac_f32_e32 v104, v52, v52
	v_fmac_f32_e32 v105, v54, v54
	v_fmac_f32_e32 v100, v16, v16
	v_fmac_f32_e32 v101, v18, v18
	v_fmac_f32_e32 v106, v56, v56
	v_fmac_f32_e32 v39, v58, v58
	v_fmac_f32_e32 v97, v60, v60
	v_fmac_f32_e32 v99, v62, v62
	v_add_f32_e32 v38, v38, v96
	v_add_f32_e32 v102, v102, v103
	v_add_f32_e32 v103, v104, v105
	v_add_f32_e32 v100, v100, v101
	v_add_f32_e32 v39, v106, v39
	v_add_f32_e32 v97, v97, v99
	v_add_f32_e32 v38, v38, v98
	s_waitcnt vmcnt(3)
	v_mul_f32_e32 v98, v81, v81
	v_mul_f32_e32 v99, v83, v83
	s_waitcnt vmcnt(2)
	v_mul_f32_e32 v104, v85, v85
	v_mul_f32_e32 v105, v87, v87
	v_add_f32_e32 v102, v102, v103
	v_mul_f32_e32 v101, v65, v65
	v_mul_f32_e32 v96, v67, v67
	v_mul_f32_e32 v107, v69, v69
	v_mul_f32_e32 v108, v71, v71
	v_add_f32_e32 v38, v38, v100
	v_fmac_f32_e32 v98, v80, v80
	v_fmac_f32_e32 v99, v82, v82
	v_fmac_f32_e32 v104, v84, v84
	v_fmac_f32_e32 v105, v86, v86
	v_add_f32_e32 v39, v102, v39
	v_fmac_f32_e32 v101, v64, v64
	v_fmac_f32_e32 v96, v66, v66
	v_fmac_f32_e32 v107, v68, v68
	v_fmac_f32_e32 v108, v70, v70
	s_waitcnt vmcnt(1)
	v_mul_f32_e32 v106, v89, v89
	v_mul_f32_e32 v113, v91, v91
	ds_bpermute_b32 v100, v42, v38
	v_add_f32_e32 v98, v98, v99
	v_add_f32_e32 v99, v104, v105
	v_add_f32_e32 v39, v39, v97
	v_mul_f32_e32 v109, v73, v73
	v_mul_f32_e32 v110, v75, v75
	s_waitcnt vmcnt(0)
	v_mul_f32_e32 v114, v93, v93
	v_mul_f32_e32 v115, v95, v95
	v_add_f32_e32 v96, v101, v96
	v_add_f32_e32 v101, v107, v108
	v_fmac_f32_e32 v106, v88, v88
	v_fmac_f32_e32 v113, v90, v90
	v_add_f32_e32 v97, v98, v99
	ds_bpermute_b32 v98, v42, v39
	v_mul_f32_e32 v111, v77, v77
	v_mul_f32_e32 v112, v79, v79
	v_fmac_f32_e32 v109, v72, v72
	v_fmac_f32_e32 v110, v74, v74
	v_fmac_f32_e32 v114, v92, v92
	v_fmac_f32_e32 v115, v94, v94
	v_add_f32_e32 v96, v96, v101
	v_add_f32_e32 v101, v106, v113
	v_fmac_f32_e32 v111, v76, v76
	v_fmac_f32_e32 v112, v78, v78
	v_add_f32_e32 v103, v109, v110
	v_add_f32_e32 v102, v114, v115
	v_add_f32_e32 v97, v97, v101
	v_add_f32_e32 v107, v111, v112
	v_add_f32_e32 v96, v96, v103
	v_add_f32_e32 v97, v97, v102
	v_add_f32_e32 v96, v96, v107
	ds_bpermute_b32 v101, v42, v97
	s_waitcnt lgkmcnt(2)
	v_add_f32_e32 v38, v38, v100
	ds_bpermute_b32 v99, v42, v96
	ds_bpermute_b32 v100, v43, v38
	s_waitcnt lgkmcnt(3)
	v_add_f32_e32 v39, v39, v98
	ds_bpermute_b32 v98, v43, v39
	s_waitcnt lgkmcnt(3)
	v_add_f32_e32 v97, v97, v101
	s_waitcnt lgkmcnt(2)
	v_add_f32_e32 v96, v96, v99
	ds_bpermute_b32 v101, v43, v97
	s_waitcnt lgkmcnt(2)
	v_add_f32_e32 v38, v38, v100
	ds_bpermute_b32 v99, v43, v96
	ds_bpermute_b32 v100, v44, v38
	s_waitcnt lgkmcnt(3)
	v_add_f32_e32 v39, v39, v98
	ds_bpermute_b32 v98, v44, v39
	s_waitcnt lgkmcnt(3)
	v_add_f32_e32 v97, v97, v101
	s_waitcnt lgkmcnt(2)
	v_add_f32_e32 v96, v96, v99
	ds_bpermute_b32 v101, v44, v97
	s_waitcnt lgkmcnt(2)
	v_add_f32_e32 v38, v38, v100
	ds_bpermute_b32 v99, v44, v96
	ds_bpermute_b32 v100, v45, v38
	s_waitcnt lgkmcnt(3)
	v_add_f32_e32 v39, v39, v98
	ds_bpermute_b32 v98, v45, v39
	s_waitcnt lgkmcnt(3)
	v_add_f32_e32 v97, v97, v101
	s_waitcnt lgkmcnt(2)
	v_add_f32_e32 v96, v96, v99
	ds_bpermute_b32 v101, v45, v97
	s_waitcnt lgkmcnt(2)
	v_add_f32_e32 v38, v38, v100
	ds_bpermute_b32 v99, v45, v96
	ds_bpermute_b32 v100, v46, v38
	s_waitcnt lgkmcnt(3)
; __device__ __forceinline__ unsigned cvtpk(float lo, float hi) { unsigned r; asm volatile("v_cvt_pk_bf16_f32 %0, %1, %2" : "=v"(r) : "v"(lo), "v"(hi)); return r; }
; __device__ __forceinline__ void p0_prologue(const Args& a, LAS unsigned char* ldsb, int G, int c, const int wid_s) {
;     ...
;       for (int q = 0; q < 4; ++q) s += (v[rr][q].x * v[rr][q].x + v[rr][q].y * v[rr][q].y) + (v[rr][q].z * v[rr][q].z + v[rr][q].w * v[rr][q].w);
;       ss[rr] = s; }
; #pragma unroll
;     for (int o = 1; o < 64; o <<= 1) {
; #pragma unroll
;       for (int rr = 0; rr < 4; ++rr) ss[rr] += __shfl_xor(ss[rr], o); }
; #pragma unroll
;     for (int rr = 0; rr < 4; ++rr) { const float rstd = __builtin_amdgcn_rsqf(ss[rr] * (1.0f / DM) + NORM_EPS);
;       u32x2* o8 = (u32x2*)(H + (size_t)(m0 + rr) * DM) + lane;
; #pragma unroll
;       for (int q = 0; q < 4; ++q) { u32x2 w; w.x = cvtpk(v[rr][q].x * rstd * gn[q].x, v[rr][q].y * rstd * gn[q].y); w.y = cvtpk(v[rr][q].z * rstd * gn[q].z, v[rr][q].w * rstd * gn[q].w); o8[64 * q] = w; } }
	v_add_f32_e32 v39, v39, v98
	ds_bpermute_b32 v98, v46, v39
	s_waitcnt lgkmcnt(3)
	v_add_f32_e32 v97, v97, v101
	s_waitcnt lgkmcnt(2)
	v_add_f32_e32 v96, v96, v99
	ds_bpermute_b32 v101, v46, v97
	s_waitcnt lgkmcnt(2)
	v_add_f32_e32 v38, v38, v100
	ds_bpermute_b32 v99, v46, v96
	ds_bpermute_b32 v100, v47, v38
	s_waitcnt lgkmcnt(3)
	v_add_f32_e32 v39, v39, v98
	ds_bpermute_b32 v98, v47, v39
	s_waitcnt lgkmcnt(3)
	v_add_f32_e32 v97, v97, v101
	s_waitcnt lgkmcnt(2)
	v_add_f32_e32 v96, v96, v99
	ds_bpermute_b32 v101, v47, v97
	s_waitcnt lgkmcnt(2)
	v_add_f32_e32 v38, v38, v100
	ds_bpermute_b32 v99, v47, v96
	v_fmamk_f32 v38, v38, 0x3a800000, v33
	s_waitcnt lgkmcnt(2)
	v_add_f32_e32 v39, v39, v98
	v_rsq_f32_e32 v38, v38
	v_fmamk_f32 v39, v39, 0x3a800000, v33
	v_rsq_f32_e32 v39, v39
	s_waitcnt lgkmcnt(1)
	v_add_f32_e32 v97, v97, v101
	s_waitcnt lgkmcnt(0)
	v_add_f32_e32 v96, v96, v99
	v_fmamk_f32 v97, v97, 0x3a800000, v33
	v_mul_f32_e32 v16, v16, v38
	v_mul_f32_e32 v17, v17, v38
	v_fmamk_f32 v96, v96, 0x3a800000, v33
	v_mul_f32_e32 v28, v28, v38
	v_mul_f32_e32 v29, v29, v38
	v_mul_f32_e32 v30, v30, v38
	v_mul_f32_e32 v31, v31, v38
	v_mul_f32_e32 v24, v24, v38
	v_mul_f32_e32 v25, v25, v38
	v_mul_f32_e32 v26, v26, v38
	v_mul_f32_e32 v27, v27, v38
	v_mul_f32_e32 v20, v20, v38
	v_mul_f32_e32 v21, v21, v38
	v_mul_f32_e32 v22, v22, v38
	v_mul_f32_e32 v23, v23, v38
	v_mul_f32_e32 v18, v18, v38
	v_mul_f32_e32 v19, v19, v38
	v_rsq_f32_e32 v38, v97
	v_mul_f32_e32 v97, v0, v16
	v_mul_f32_e32 v98, v1, v17
	v_mul_f32_e32 v16, v48, v39
	v_mul_f32_e32 v17, v49, v39
	v_rsq_f32_e32 v96, v96
	v_mul_f32_e32 v48, v50, v39
	v_mul_f32_e32 v49, v51, v39
	v_mul_f32_e32 v16, v12, v16
	v_mul_f32_e32 v17, v13, v17
	v_mul_f32_e32 v50, v52, v39
	v_mul_f32_e32 v51, v53, v39
	v_mul_f32_e32 v52, v54, v39
	v_mul_f32_e32 v53, v55, v39
	v_mul_f32_e32 v48, v14, v48
	v_mul_f32_e32 v49, v15, v49
	v_cvt_pk_bf16_f32 v16, v16, v17
	v_cvt_pk_bf16_f32 v17, v48, v49
	v_mul_f32_e32 v54, v56, v39
	v_mul_f32_e32 v55, v57, v39
	v_mul_f32_e32 v56, v58, v39
	v_mul_f32_e32 v57, v59, v39
	v_mul_f32_e32 v50, v8, v50
	v_mul_f32_e32 v51, v9, v51
	v_mul_f32_e32 v52, v10, v52
	v_mul_f32_e32 v53, v11, v53
	global_store_dwordx2 v[40:41], v[16:17], off offset:-3584
	v_cvt_pk_bf16_f32 v16, v50, v51
	v_cvt_pk_bf16_f32 v17, v52, v53
	v_mul_f32_e32 v58, v60, v39
	v_mul_f32_e32 v59, v61, v39
	v_mul_f32_e32 v60, v62, v39
	v_mul_f32_e32 v39, v63, v39
	v_mul_f32_e32 v54, v4, v54
	v_mul_f32_e32 v55, v5, v55
	v_mul_f32_e32 v56, v6, v56
	v_mul_f32_e32 v57, v7, v57
	global_store_dwordx2 v[40:41], v[16:17], off offset:-3072
	v_cvt_pk_bf16_f32 v16, v54, v55
	v_cvt_pk_bf16_f32 v17, v56, v57
	v_mul_f32_e32 v61, v64, v96
	v_mul_f32_e32 v62, v65, v96
	v_mul_f32_e32 v63, v66, v96
	v_mul_f32_e32 v64, v67, v96
	v_mul_f32_e32 v58, v0, v58
	v_mul_f32_e32 v59, v1, v59
	v_mul_f32_e32 v60, v2, v60
	v_mul_f32_e32 v39, v3, v39
	global_store_dwordx2 v[40:41], v[16:17], off offset:-2560
	v_cvt_pk_bf16_f32 v16, v58, v59
	v_cvt_pk_bf16_f32 v17, v60, v39
	v_mul_f32_e32 v65, v68, v96
	v_mul_f32_e32 v66, v69, v96
	v_mul_f32_e32 v67, v70, v96
	v_mul_f32_e32 v68, v71, v96
	v_mul_f32_e32 v48, v12, v61
	v_mul_f32_e32 v49, v13, v62
	v_mul_f32_e32 v61, v14, v63
	v_mul_f32_e32 v62, v15, v64
	global_store_dwordx2 v[40:41], v[16:17], off offset:-2048
	v_cvt_pk_bf16_f32 v16, v48, v49
	v_cvt_pk_bf16_f32 v17, v61, v62
	v_mul_f32_e32 v69, v72, v96
	v_mul_f32_e32 v70, v73, v96
	v_mul_f32_e32 v71, v74, v96
	v_mul_f32_e32 v72, v75, v96
	v_mul_f32_e32 v63, v8, v65
	v_mul_f32_e32 v64, v9, v66
	v_mul_f32_e32 v65, v10, v67
	v_mul_f32_e32 v66, v11, v68
	global_store_dwordx2 v[40:41], v[16:17], off offset:-1536
	v_cvt_pk_bf16_f32 v16, v63, v64
	v_cvt_pk_bf16_f32 v17, v65, v66
	v_mul_f32_e32 v73, v76, v96
	v_mul_f32_e32 v74, v77, v96
	v_mul_f32_e32 v75, v78, v96
	v_mul_f32_e32 v76, v79, v96
	v_mul_f32_e32 v67, v4, v69
	v_mul_f32_e32 v68, v5, v70
	v_mul_f32_e32 v69, v6, v71
	v_mul_f32_e32 v70, v7, v72
	global_store_dwordx2 v[40:41], v[16:17], off offset:-1024
	v_cvt_pk_bf16_f32 v16, v67, v68
	v_cvt_pk_bf16_f32 v17, v69, v70
	v_mul_f32_e32 v77, v80, v38
	v_mul_f32_e32 v78, v81, v38
	v_mul_f32_e32 v79, v82, v38
	v_mul_f32_e32 v80, v83, v38
	v_mul_f32_e32 v71, v0, v73
	v_mul_f32_e32 v72, v1, v74
	v_mul_f32_e32 v73, v2, v75
	v_mul_f32_e32 v74, v3, v76
	global_store_dwordx2 v[40:41], v[16:17], off offset:-512
	v_cvt_pk_bf16_f32 v16, v71, v72
	v_cvt_pk_bf16_f32 v17, v73, v74
	v_mul_f32_e32 v81, v84, v38
	v_mul_f32_e32 v82, v85, v38
	v_mul_f32_e32 v83, v86, v38
	v_mul_f32_e32 v84, v87, v38
	v_mul_f32_e32 v50, v12, v77
	v_mul_f32_e32 v51, v13, v78
	v_mul_f32_e32 v52, v14, v79
	v_mul_f32_e32 v53, v15, v80
	global_store_dwordx2 v[34:35], v[16:17], off offset:-4096
	v_cvt_pk_bf16_f32 v16, v50, v51
	v_cvt_pk_bf16_f32 v17, v52, v53
	v_mul_f32_e32 v85, v88, v38
	v_mul_f32_e32 v86, v89, v38
	v_mul_f32_e32 v87, v90, v38
	v_mul_f32_e32 v88, v91, v38
	v_mul_f32_e32 v75, v8, v81
	v_mul_f32_e32 v76, v9, v82
	v_mul_f32_e32 v77, v10, v83
	v_mul_f32_e32 v78, v11, v84
	global_store_dwordx2 v[34:35], v[16:17], off offset:-3584
	v_cvt_pk_bf16_f32 v16, v75, v76
	v_cvt_pk_bf16_f32 v17, v77, v78
	v_mul_f32_e32 v89, v92, v38
	v_mul_f32_e32 v90, v93, v38
	v_mul_f32_e32 v91, v94, v38
	v_mul_f32_e32 v38, v95, v38
	v_mul_f32_e32 v79, v4, v85
	v_mul_f32_e32 v80, v5, v86
	v_mul_f32_e32 v81, v6, v87
	v_mul_f32_e32 v82, v7, v88
	global_store_dwordx2 v[34:35], v[16:17], off offset:-3072
	v_cvt_pk_bf16_f32 v16, v79, v80
	v_cvt_pk_bf16_f32 v17, v81, v82
	v_mul_f32_e32 v83, v0, v89
	v_mul_f32_e32 v84, v1, v90
	v_mul_f32_e32 v85, v2, v91
	v_mul_f32_e32 v38, v3, v38
	global_store_dwordx2 v[34:35], v[16:17], off offset:-2560
	v_cvt_pk_bf16_f32 v16, v83, v84
	v_cvt_pk_bf16_f32 v17, v85, v38
	v_mul_f32_e32 v28, v12, v28
	v_mul_f32_e32 v29, v13, v29
	v_mul_f32_e32 v30, v14, v30
	v_mul_f32_e32 v31, v15, v31
	global_store_dwordx2 v[34:35], v[16:17], off offset:-2048
	v_cvt_pk_bf16_f32 v16, v28, v29
	v_cvt_pk_bf16_f32 v17, v30, v31
	v_mul_f32_e32 v24, v8, v24
	v_mul_f32_e32 v25, v9, v25
	v_mul_f32_e32 v26, v10, v26
	v_mul_f32_e32 v27, v11, v27
	global_store_dwordx2 v[34:35], v[16:17], off offset:-1536
	v_cvt_pk_bf16_f32 v16, v24, v25
	v_cvt_pk_bf16_f32 v17, v26, v27
	v_mul_f32_e32 v20, v4, v20
	v_mul_f32_e32 v21, v5, v21
	v_mul_f32_e32 v22, v6, v22
	v_mul_f32_e32 v23, v7, v23
	global_store_dwordx2 v[34:35], v[16:17], off offset:-1024
	v_cvt_pk_bf16_f32 v16, v20, v21
	v_cvt_pk_bf16_f32 v17, v22, v23
	v_mul_f32_e32 v18, v2, v18
	v_mul_f32_e32 v19, v3, v19
	global_store_dwordx2 v[34:35], v[16:17], off offset:-512
	v_cvt_pk_bf16_f32 v16, v97, v98
	v_cvt_pk_bf16_f32 v17, v18, v19
	global_store_dwordx2 v[34:35], v[16:17], off
	v_lshl_add_u64 v[34:35], v[34:35], 0, s[14:15]
	s_andn2_b64 exec, exec, s[22:23]
	s_cbranch_execnz .LBB0_94
